# GU epilogue SiLU-gate rewritten with packed f32 multiplies and batched row-scale reduction; same operations and rounding
# speedup vs baseline: 1.0122x; 1.0122x over previous
; #define LAS __attribute__((address_space(3)))
; #define GLA_SPIN(cond) do { unsigned sp_ = 0; while ((cond) && ++sp_ < (1u << 22)) __builtin_amdgcn_s_sleep(1); } while (0)
; __device__ __forceinline__ void gla_seq_phase(const bf16* QDP, const bf16* KST, const bf16* ATT, const bf16* VT2, const float* DEC, float* OG, LAS unsigned char* lds, int tid, int wave, int lane, int G) {
;     volatile LAS unsigned* flags = (volatile LAS unsigned*)(lds + 16384);
;     if (tid < 4) flags[tid] = 0u;
;     __syncthreads();
;     const int unit = blockIdx.x;
;     if (wave >= 3 || unit >= 256) return;
;     ...
;         const int mb = wave - 1;
;         const bf16* attb = ATT + u0 * 4096 + (size_t)(32 * mb + ql) * 64 + 8 * hi; const bf16* qdb = QDP + u0 * 8192 + (size_t)(32 * mb + ql) * 128 + 8 * hi;
;         bf16x8_t vf[4], af[4], qf[8];
; #pragma unroll
;         for (int st = 0; st < 4; ++st) { vf[st] = *(const bf16x8_t*)(vtb + 16 * st); af[st] = *(const bf16x8_t*)(attb + 16 * st); }
; #pragma unroll
;         for (int st = 0; st < 8; ++st) qf[st] = *(const bf16x8_t*)(qdb + 16 * st);
;         for (int n = 0; n < GLA_NCH; ++n) {
;             const int nn = n + 1 < GLA_NCH ? n + 1 : n;
;             f32x16 o;
; #pragma unroll
;             for (int r = 0; r < 16; ++r) o[r] = 0.f;
; #pragma unroll
;             for (int st = 0; st < 4; ++st) o = __builtin_amdgcn_mfma_f32_32x32x16_bf16(af[st], vf[st], o, 0, 0, 0);
; #pragma unroll
;             for (int st = 0; st < 4; ++st) { af[st] = *(const bf16x8_t*)(attb + (size_t)nn * 4 * 4096 + 16 * st); vf[st] = *(const bf16x8_t*)(vtb + (size_t)nn * 4 * 16384 + 16 * st); }
;             GLA_SPIN(flags[0] < (unsigned)(n + 1));
.LBB0_33:
	v_readlane_b32 s3, v249, 40
	s_cmp_lg_u32 s10, s3
	v_readlane_b32 s3, v249, 38
	s_cselect_b64 s[80:81], -1, 0
	s_cmp_ge_u32 s10, s3
	s_mov_b64 s[6:7], -1
	s_cselect_b64 s[96:97], -1, 0
	s_mov_b64 s[86:87], 0
	s_cmp_lt_i32 s57, 4
	s_mov_b64 s[84:85], 0
	s_mov_b64 s[74:75], 0
	s_mov_b64 s[46:47], 0
	v_writelane_b32 v248, s10, 7
	s_cbranch_scc1 .LBB0_229
	s_mov_b64 s[70:71], -1
	s_cmp_gt_i32 s57, 5
	s_cbranch_scc0 .LBB0_185
	s_mov_b64 s[46:47], -1
	s_mov_b64 s[70:71], 0
	s_cmp_gt_i32 s57, 6
	s_cbranch_scc0 .LBB0_185
	v_readlane_b32 s22, v249, 8
	s_cmp_gt_i32 s57, 7
	v_readlane_b32 s23, v249, 9
	v_writelane_b32 v248, s96, 8
	s_nop 1
	v_writelane_b32 v248, s97, 9
	s_cbranch_scc0 .LBB0_63
	s_cmp_eq_u32 s57, 8
	s_cbranch_scc0 .LBB0_154
	v_mov_b32_e32 v0, v208
	s_mov_b64 s[6:7], s[0:1]
	s_load_dwordx2 s[14:15], s[6:7], 0x98
	s_mov_b64 s[6:7], s[0:1]
	s_load_dwordx2 s[10:11], s[6:7], 0x98
	s_mov_b64 s[6:7], s[0:1]
	s_waitcnt lgkmcnt(0)
	s_load_dwordx2 s[16:17], s[6:7], 0x98
	s_mov_b64 s[6:7], s[0:1]
	s_mov_b64 s[8:9], s[0:1]
	s_load_dwordx2 s[6:7], s[6:7], 0x98
	s_mov_b64 s[12:13], s[0:1]
	s_load_dwordx2 s[8:9], s[8:9], 0x98
	s_load_dwordx2 s[12:13], s[12:13], 0x98
	v_cmp_gt_i32_e32 vcc, 4, v0
	s_and_saveexec_b64 s[18:19], vcc
	v_lshl_add_u32 v1, v0, 2, 0
	ds_write_b32 v1, v211 offset:16384
	s_or_b64 exec, exec, s[18:19]
	v_readlane_b32 s18, v250, 22
	v_readlane_b32 s19, v250, 23
	v_readlane_b32 s44, v249, 48
	s_andn2_b64 vcc, exec, s[18:19]
	v_readlane_b32 s20, v250, 34
	v_readlane_b32 s21, v249, 21
	v_readlane_b32 s42, v249, 46
	v_readlane_b32 s43, v249, 47
	v_readlane_b32 s45, v249, 49
	v_readlane_b32 s46, v249, 56
	s_waitcnt lgkmcnt(0)
	s_barrier
	s_cbranch_vccnz .LBB0_79
	s_waitcnt vmcnt(0)
	v_and_b32_e32 v123, 31, v0
	v_readlane_b32 s18, v250, 24
	v_readlane_b32 s3, v250, 26
	v_readlane_b32 s19, v250, 25
	s_add_u32 s6, s6, s18
	v_or_b32_e32 v1, s3, v123
	v_and_b32_e32 v122, 63, v0
	v_bfe_u32 v0, v0, 5, 1
	s_addc_u32 s7, s7, s19
	v_lshlrev_b32_e32 v210, 7, v1
	v_lshl_add_u64 v[2:3], s[6:7], 0, v[210:211]
	v_lshlrev_b32_e32 v112, 4, v0
	v_mov_b32_e32 v113, v211
	v_lshl_add_u64 v[2:3], v[2:3], 0, v[112:113]
	s_mov_b64 s[6:7], 0x15700000
	v_lshl_add_u64 v[212:213], v[2:3], 0, s[6:7]
	v_readlane_b32 s6, v250, 27
	v_lshlrev_b32_e32 v1, 3, v0
	v_readlane_b32 s7, v250, 28
	s_mov_b64 s[18:19], -1
	s_and_b64 vcc, exec, s[6:7]
	v_lshlrev_b32_e32 v114, 1, v1
	v_lshl_add_u32 v226, v122, 4, 0
	v_cmp_eq_u32_e64 s[6:7], 0, v122
	s_cbranch_vccz .LBB0_65
	v_readlane_b32 s3, v250, 31
	v_readlane_b32 s18, v250, 29
	v_readlane_b32 s19, v250, 30
	v_or_b32_e32 v2, s3, v123
	s_add_u32 s16, s16, s18
	v_ashrrev_i32_e32 v3, 31, v2
	s_addc_u32 s17, s17, s19
	v_lshlrev_b64 v[4:5], 7, v[2:3]
	v_lshl_add_u64 v[4:5], s[16:17], 0, v[4:5]
	v_mov_b32_e32 v115, v211
	v_lshl_add_u64 v[4:5], v[4:5], 0, v[114:115]
	s_mov_b64 s[16:17], 0x17800000
	v_lshl_add_u64 v[116:117], v[4:5], 0, s[16:17]
	v_readlane_b32 s16, v250, 32
	v_readlane_b32 s17, v250, 33
	s_add_u32 s14, s14, s16
	s_addc_u32 s15, s15, s17
	v_lshlrev_b64 v[2:3], 8, v[2:3]
	s_mov_b32 s3, 0x17800000
	v_lshl_add_u64 v[2:3], s[14:15], 0, v[2:3]
	v_add_co_u32_e32 v4, vcc, s3, v4
	v_lshl_add_u64 v[2:3], v[2:3], 0, v[114:115]
	s_nop 0
	v_addc_co_u32_e32 v5, vcc, 0, v5, vcc
	s_mov_b64 s[14:15], 0xf400000
	s_mov_b32 s3, 0xf400000
	v_lshl_add_u64 v[118:119], v[2:3], 0, s[14:15]
	v_add_co_u32_e32 v2, vcc, s3, v2
	global_load_dwordx4 v[24:27], v[4:5], off
	global_load_dwordx4 v[16:19], v[212:213], off
	global_load_dwordx4 v[20:23], v[212:213], off offset:32
	global_load_dwordx4 v[28:31], v[116:117], off offset:32
	global_load_dwordx4 v[32:35], v[116:117], off offset:64
	global_load_dwordx4 v[36:39], v[212:213], off offset:64
	global_load_dwordx4 v[40:43], v[212:213], off offset:96
	global_load_dwordx4 v[44:47], v[116:117], off offset:96
	v_addc_co_u32_e32 v3, vcc, 0, v3, vcc
	global_load_dwordx4 v[76:79], v[2:3], off
	global_load_dwordx4 v[72:75], v[118:119], off offset:32
	global_load_dwordx4 v[68:71], v[118:119], off offset:64
	global_load_dwordx4 v[64:67], v[118:119], off offset:96
	global_load_dwordx4 v[60:63], v[118:119], off offset:128
	global_load_dwordx4 v[56:59], v[118:119], off offset:160
	global_load_dwordx4 v[52:55], v[118:119], off offset:192
	global_load_dwordx4 v[48:51], v[118:119], off offset:224
	v_readlane_b32 s3, v249, 19
	s_add_u32 s3, s12, s3
	v_readlane_b32 s12, v250, 26
	s_addc_u32 s13, s13, 0
	s_lshl_b32 s12, s12, 2
	s_add_u32 s12, s3, s12
	s_addc_u32 s13, s13, 0
	v_lshlrev_b32_e32 v210, 2, v123
	v_lshlrev_b32_e32 v113, 2, v0
	v_lshl_add_u64 v[0:1], s[12:13], 0, v[210:211]
	s_mov_b64 s[12:13], 0x11500000
	s_mov_b32 s14, 0
	v_lshl_add_u64 v[120:121], v[0:1], 0, s[12:13]
	v_or_b32_e32 v115, 1, v113
	v_or_b32_e32 v124, 2, v113
	v_or_b32_e32 v125, 3, v113
	s_branch .LBB0_44
.LBB0_43:
	s_waitcnt vmcnt(0)
	v_mov_b64_e32 v[48:49], v[80:81]
	s_cmp_lg_u32 s3, 33
	v_mov_b64_e32 v[50:51], v[82:83]
	s_mov_b32 s14, s3
	s_cbranch_scc0 .LBB0_64
.LBB0_44:
	s_add_i32 s3, s14, 1
	s_cmp_lg_u32 s14, 32
	s_cselect_b32 s15, s3, 32
	s_lshl_b32 s76, s15, 2
	s_waitcnt vmcnt(10)
	v_mov_b64_e32 v[98:99], v[38:39]
	s_lshl_b64 s[12:13], s[76:77], 13
	v_mov_b64_e32 v[82:83], v[30:31]
	v_mov_b64_e32 v[86:87], v[34:35]
	s_waitcnt vmcnt(8)
	v_mov_b64_e32 v[90:91], v[46:47]
	v_mov_b64_e32 v[94:95], v[22:23]
	v_mov_b64_e32 v[96:97], v[36:37]
	v_mov_b64_e32 v[102:103], v[42:43]
	v_lshl_add_u64 v[36:37], v[116:117], 0, s[12:13]
	s_lshl_b64 s[12:13], s[76:77], 15
	v_mov_b64_e32 v[80:81], v[28:29]
	v_mov_b64_e32 v[84:85], v[32:33]
	v_mov_b64_e32 v[88:89], v[44:45]
	v_mov_b64_e32 v[92:93], v[20:21]
	v_mov_b64_e32 v[100:101], v[40:41]
	v_mfma_f32_32x32x16_bf16 v[0:15], v[24:27], v[16:19], 0
	v_lshl_add_u64 v[40:41], v[212:213], 0, s[12:13]
	global_load_dwordx4 v[24:27], v[36:37], off
	global_load_dwordx4 v[28:31], v[36:37], off offset:32
	global_load_dwordx4 v[16:19], v[40:41], off
	global_load_dwordx4 v[20:23], v[40:41], off offset:32
	global_load_dwordx4 v[32:35], v[36:37], off offset:64
	global_load_dwordx4 v[44:47], v[36:37], off offset:96
	s_nop 0
	global_load_dwordx4 v[36:39], v[40:41], off offset:64
	s_nop 0
	global_load_dwordx4 v[40:43], v[40:41], off offset:96
	v_mfma_f32_32x32x16_bf16 v[0:15], v[80:83], v[92:95], v[0:15]
	ds_read_b32 v80, v211 offset:16384
	s_waitcnt lgkmcnt(0)
	v_cmp_lt_u32_e32 vcc, s14, v80
	v_mfma_f32_32x32x16_bf16 v[0:15], v[84:87], v[96:99], v[0:15]
	v_mfma_f32_32x32x16_bf16 v[0:15], v[88:91], v[100:103], v[0:15]
	s_cbranch_vccnz .LBB0_55
	s_mov_b32 s16, 0x3ffff8
	s_branch .LBB0_47

; #define LAS __attribute__((address_space(3)))
; #define GLA_SPIN(cond) do { unsigned sp_ = 0; while ((cond) && ++sp_ < (1u << 22)) __builtin_amdgcn_s_sleep(1); } while (0)
; __device__ __forceinline__ void gla_seq_phase(const bf16* QDP, const bf16* KST, const bf16* ATT, const bf16* VT2, const float* DEC, float* OG, LAS unsigned char* lds, int tid, int wave, int lane, int G) {
;     ...
;             GLA_SPIN(flags[0] < (unsigned)(n + 1));
;             __builtin_amdgcn_fence(__ATOMIC_ACQUIRE, "workgroup");
;             const LAS unsigned char* slot = lds + (n & 1) * 8192 + lane * 16;
;             bf16x8_t sb[8];
; #pragma unroll
;             for (int st = 0; st < 8; ++st) sb[st] = *(const LAS bf16x8_t*)(slot + st * 1024);
;             asm volatile("s_waitcnt lgkmcnt(0)" ::: "memory");
;             if (lane == 0) flags[wave] = (unsigned)(n + 1);
; #pragma unroll
;             for (int st = 0; st < 8; ++st) o = __builtin_amdgcn_mfma_f32_32x32x16_bf16(qf[st], sb[st], o, 0, 0, 0);
; #pragma unroll
;             for (int st = 0; st < 8; ++st) qf[st] = *(const bf16x8_t*)(qdb + (size_t)nn * 4 * 8192 + 16 * st);
; #pragma unroll
;             for (int r = 0; r < 16; ++r) { const int t = 64 * n - 48 + 32 * mb + 8 * (r >> 2) + 4 * hi + (r & 3); if (t >= 0) OG[((size_t)b * L + t) * 1024 + 256 * h + 32 * vs + ql] = o[r]; }
.LBB0_55:
	s_lshl_b32 s12, s14, 13
	s_and_b32 s12, s12, 0x2000
	v_add_u32_e32 v84, s12, v226
	ds_read_b128 v[108:111], v84
	ds_read_b128 v[104:107], v84 offset:1024
	ds_read_b128 v[100:103], v84 offset:2048
	ds_read_b128 v[96:99], v84 offset:3072
	ds_read_b128 v[92:95], v84 offset:4096
	ds_read_b128 v[88:91], v84 offset:5120
	ds_read_b128 v[80:83], v84 offset:6144
	ds_read_b128 v[84:87], v84 offset:7168
	s_waitcnt lgkmcnt(0)
	s_and_saveexec_b64 s[12:13], s[6:7]
	v_mov_b32_e32 v126, s21
	v_mov_b32_e32 v127, s3
	ds_write_b32 v126, v127 offset:16384
	s_or_b64 exec, exec, s[12:13]
	s_waitcnt vmcnt(15) lgkmcnt(7)
	v_mfma_f32_32x32x16_bf16 v[0:15], v[76:79], v[108:111], v[0:15]
	s_lshl_b32 s76, s15, 16
	s_lshl_b32 s12, s14, 6
	s_add_i32 s12, s20, s12
	s_cmp_lt_i32 s12, 0
	s_waitcnt vmcnt(14) lgkmcnt(6)
	v_mfma_f32_32x32x16_bf16 v[0:15], v[72:75], v[104:107], v[0:15]
	s_waitcnt vmcnt(13) lgkmcnt(5)
	v_mfma_f32_32x32x16_bf16 v[0:15], v[68:71], v[100:103], v[0:15]
	s_waitcnt vmcnt(12) lgkmcnt(4)
	v_mfma_f32_32x32x16_bf16 v[0:15], v[64:67], v[96:99], v[0:15]
	s_waitcnt vmcnt(11) lgkmcnt(3)
	v_mfma_f32_32x32x16_bf16 v[0:15], v[60:63], v[92:95], v[0:15]
	s_waitcnt vmcnt(10) lgkmcnt(2)
	v_mfma_f32_32x32x16_bf16 v[0:15], v[56:59], v[88:91], v[0:15]
	v_lshl_add_u64 v[88:89], v[118:119], 0, s[76:77]
	global_load_dwordx4 v[76:79], v[88:89], off
	global_load_dwordx4 v[72:75], v[88:89], off offset:32
	global_load_dwordx4 v[68:71], v[88:89], off offset:64
	global_load_dwordx4 v[64:67], v[88:89], off offset:96
	global_load_dwordx4 v[60:63], v[88:89], off offset:128
	global_load_dwordx4 v[56:59], v[88:89], off offset:160
	s_waitcnt vmcnt(15) lgkmcnt(1)
	v_mfma_f32_32x32x16_bf16 v[0:15], v[52:55], v[80:83], v[0:15]
	global_load_dwordx4 v[52:55], v[88:89], off offset:192
	global_load_dwordx4 v[80:83], v[88:89], off offset:224
	s_waitcnt vmcnt(16) lgkmcnt(0)
	v_mfma_f32_32x32x16_bf16 v[0:15], v[48:51], v[84:87], v[0:15]
	s_cbranch_scc1 .LBB0_59
	v_or_b32_e32 v210, s12, v113
	v_lshl_add_u64 v[48:49], s[22:23], 0, v[210:211]
	v_lshlrev_b64 v[48:49], 12, v[48:49]
	v_lshl_add_u64 v[48:49], v[120:121], 0, v[48:49]
	v_or_b32_e32 v210, s12, v115
	s_nop 5
	global_store_dword v[48:49], v0, off
	v_lshl_add_u64 v[48:49], s[22:23], 0, v[210:211]
	v_lshlrev_b64 v[48:49], 12, v[48:49]
	v_lshl_add_u64 v[48:49], v[120:121], 0, v[48:49]
	v_or_b32_e32 v210, s12, v124
	global_store_dword v[48:49], v1, off
	v_lshl_add_u64 v[0:1], s[22:23], 0, v[210:211]
	v_lshlrev_b64 v[0:1], 12, v[0:1]
	v_lshl_add_u64 v[0:1], v[120:121], 0, v[0:1]
	v_or_b32_e32 v210, s12, v125
	global_store_dword v[0:1], v2, off
	v_lshl_add_u64 v[0:1], s[22:23], 0, v[210:211]
	v_lshlrev_b64 v[0:1], 12, v[0:1]
	s_or_b32 s13, s12, 8
	v_lshl_add_u64 v[0:1], v[120:121], 0, v[0:1]
	v_or_b32_e32 v210, s13, v113
	global_store_dword v[0:1], v3, off
	v_lshl_add_u64 v[0:1], s[22:23], 0, v[210:211]
	v_lshlrev_b64 v[0:1], 12, v[0:1]
	v_lshl_add_u64 v[0:1], v[120:121], 0, v[0:1]
	v_or_b32_e32 v210, s13, v115
	global_store_dword v[0:1], v4, off
	v_lshl_add_u64 v[0:1], s[22:23], 0, v[210:211]
	v_lshlrev_b64 v[0:1], 12, v[0:1]
	v_lshl_add_u64 v[0:1], v[120:121], 0, v[0:1]
	v_or_b32_e32 v210, s13, v124
	global_store_dword v[0:1], v5, off
	v_lshl_add_u64 v[0:1], s[22:23], 0, v[210:211]
	v_lshlrev_b64 v[0:1], 12, v[0:1]
	v_lshl_add_u64 v[0:1], v[120:121], 0, v[0:1]
	v_or_b32_e32 v210, s13, v125
	global_store_dword v[0:1], v6, off
	v_lshl_add_u64 v[0:1], s[22:23], 0, v[210:211]
	v_lshlrev_b64 v[0:1], 12, v[0:1]
	v_lshl_add_u64 v[0:1], v[120:121], 0, v[0:1]
	global_store_dword v[0:1], v7, off

; #define LAS __attribute__((address_space(3)))
; __device__ __forceinline__ void gla_seq_phase(const bf16* QDP, const bf16* KST, const bf16* ATT, const bf16* VT2, const float* DEC, float* OG, LAS unsigned char* lds, int tid, int wave, int lane, int G) {
;     ...
;     if (wave == 0) {
;         const bf16* ksb = KST + u0 * 8192 + ql * 64 + 8 * hi; const float* decb = DEC + u0 * 128 + 4 * hi;
;         f32x16 S0, S1, S2, S3;
; #pragma unroll
;         for (int r = 0; r < 16; ++r) { S0[r] = 0.f; S1[r] = 0.f; S2[r] = 0.f; S3[r] = 0.f; }
;         bf16x8_t vf[4], k0[4], k1[4], k2[4], k3[4]; f32x4 d0[4], d1[4], d2[4], d3[4];
; #pragma unroll
;         for (int st = 0; st < 4; ++st) { vf[st] = *(const bf16x8_t*)(vtb + 16 * st); k0[st] = *(const bf16x8_t*)(ksb + 16 * st); k1[st] = *(const bf16x8_t*)(ksb + 2048 + 16 * st);
;             k2[st] = *(const bf16x8_t*)(ksb + 4096 + 16 * st); k3[st] = *(const bf16x8_t*)(ksb + 6144 + 16 * st);
;             d0[st] = *(const f32x4*)(decb + 8 * st); d1[st] = *(const f32x4*)(decb + 32 + 8 * st); d2[st] = *(const f32x4*)(decb + 64 + 8 * st); d3[st] = *(const f32x4*)(decb + 96 + 8 * st); }
;         for (int n = 0; n < GLA_NCH; ++n) {
;             if (n >= 2) { GLA_SPIN(flags[1] < (unsigned)(n - 1) || flags[2] < (unsigned)(n - 1)); }
;             LAS unsigned char* slot = lds + (n & 1) * 8192 + lane * 16;
;             *(LAS bf16x8_t*)(slot + 0 * 1024) = gla_pack(S0, 0); *(LAS bf16x8_t*)(slot + 1 * 1024) = gla_pack(S0, 1); *(LAS bf16x8_t*)(slot + 2 * 1024) = gla_pack(S1, 0); *(LAS bf16x8_t*)(slot + 3 * 1024) = gla_pack(S1, 1);
;             *(LAS bf16x8_t*)(slot + 4 * 1024) = gla_pack(S2, 0); *(LAS bf16x8_t*)(slot + 5 * 1024) = gla_pack(S2, 1); *(LAS bf16x8_t*)(slot + 6 * 1024) = gla_pack(S3, 0); *(LAS bf16x8_t*)(slot + 7 * 1024) = gla_pack(S3, 1);
;             __builtin_amdgcn_fence(__ATOMIC_RELEASE, "workgroup");
;             if (lane == 0) flags[0] = (unsigned)(n + 1);
;             const int nn = n + 1 < GLA_NCH ? n + 1 : n;
;             const bf16* ksn = ksb + (size_t)nn * 4 * 8192; const float* decn = decb + (size_t)nn * 4 * 128; const bf16* vtn = vtb + (size_t)nn * 4 * 16384;
;     ...
;             GLA_SUPD(S0, k0, d0, 0); GLA_SUPD(S1, k1, d1, 1); GLA_SUPD(S2, k2, d2, 2); GLA_SUPD(S3, k3, d3, 3);
;     ...
; #pragma unroll
;             for (int st = 0; st < 4; ++st) vf[st] = *(const bf16x8_t*)(vtn + 16 * st);
;         }
.LBB0_65:
	s_and_b64 vcc, exec, s[18:19]
	s_cbranch_vccz .LBB0_79
	v_readlane_b32 s6, v250, 32
	v_readlane_b32 s7, v250, 33
	s_add_u32 s6, s10, s6
	s_addc_u32 s7, s11, s7
	v_lshlrev_b32_e32 v210, 7, v123
	v_lshl_add_u64 v[0:1], s[6:7], 0, v[210:211]
	v_mov_b32_e32 v115, v211
	v_lshl_add_u64 v[0:1], v[0:1], 0, v[114:115]
	s_mov_b64 s[6:7], 0x300000
	v_lshl_add_u64 v[214:215], v[0:1], 0, s[6:7]
	v_readlane_b32 s6, v250, 35
	v_readlane_b32 s7, v250, 36
	s_add_u32 s6, s8, s6
	s_addc_u32 s7, s9, s7
	v_mov_b32_e32 v113, v211
	v_lshl_add_u64 v[0:1], s[6:7], 0, v[112:113]
	s_mov_b64 s[6:7], 0x18100000
	v_lshl_add_u64 v[216:217], v[0:1], 0, s[6:7]
	v_mov_b32_e32 v0, 0
	s_mov_b32 s3, 0
	v_cmp_eq_u32_e64 s[6:7], 0, v122
	v_mov_b64_e32 v[88:89], v[216:217]
	v_mov_b64_e32 v[168:169], v[214:215]
	v_mov_b64_e32 v[80:81], v[212:213]
	v_mov_b32_e32 v1, v0
	v_mov_b32_e32 v2, v0
	v_mov_b32_e32 v3, v0
	v_mov_b32_e32 v4, v0
	v_mov_b32_e32 v5, v0
	v_mov_b32_e32 v6, v0
	v_mov_b32_e32 v7, v0
	v_mov_b32_e32 v8, v0
	v_mov_b32_e32 v9, v0
	v_mov_b32_e32 v10, v0
	v_mov_b32_e32 v11, v0
	v_mov_b32_e32 v12, v0
	v_mov_b32_e32 v13, v0
	v_mov_b32_e32 v14, v0
	v_mov_b32_e32 v15, v0
	v_mov_b32_e32 v16, v0
	v_mov_b32_e32 v17, v0
	v_mov_b32_e32 v18, v0
	v_mov_b32_e32 v19, v0
	v_mov_b32_e32 v20, v0
	v_mov_b32_e32 v21, v0
	v_mov_b32_e32 v22, v0
	v_mov_b32_e32 v23, v0
	v_mov_b32_e32 v24, v0
	v_mov_b32_e32 v25, v0
	v_mov_b32_e32 v26, v0
	v_mov_b32_e32 v27, v0
	v_mov_b32_e32 v28, v0
	v_mov_b32_e32 v29, v0
	v_mov_b32_e32 v30, v0
	v_mov_b32_e32 v31, v0
	v_mov_b32_e32 v32, v0
	v_mov_b32_e32 v33, v0
	v_mov_b32_e32 v34, v0
	v_mov_b32_e32 v35, v0
	v_mov_b32_e32 v36, v0
	v_mov_b32_e32 v37, v0
	v_mov_b32_e32 v38, v0
	v_mov_b32_e32 v39, v0
	v_mov_b32_e32 v40, v0
	v_mov_b32_e32 v41, v0
	v_mov_b32_e32 v42, v0
	v_mov_b32_e32 v43, v0
	v_mov_b32_e32 v44, v0
	v_mov_b32_e32 v45, v0
	v_mov_b32_e32 v46, v0
	v_mov_b32_e32 v47, v0
	v_mov_b32_e32 v48, v0
	v_mov_b32_e32 v49, v0
	v_mov_b32_e32 v50, v0
	v_mov_b32_e32 v51, v0
	v_mov_b32_e32 v52, v0
	v_mov_b32_e32 v53, v0
	v_mov_b32_e32 v54, v0
	v_mov_b32_e32 v55, v0
	v_mov_b32_e32 v56, v0
	v_mov_b32_e32 v57, v0
	v_mov_b32_e32 v58, v0
	v_mov_b32_e32 v59, v0
	v_mov_b32_e32 v60, v0
	v_mov_b32_e32 v61, v0
	v_mov_b32_e32 v62, v0
	v_mov_b32_e32 v63, v0
	s_branch .LBB0_68
.LBB0_67:
	s_or_b64 exec, exec, s[8:9]
	s_waitcnt vmcnt(12)
	v_pk_mul_f32 v[14:15], v[14:15], v[206:207]
	v_pk_mul_f32 v[10:11], v[10:11], v[198:199]
	v_pk_mul_f32 v[6:7], v[6:7], v[194:195]
	v_pk_mul_f32 v[2:3], v[2:3], v[202:203]
	v_pk_mul_f32 v[0:1], v[0:1], v[200:201]
	v_pk_mul_f32 v[12:13], v[12:13], v[204:205]
	v_pk_mul_f32 v[8:9], v[8:9], v[196:197]
	v_pk_mul_f32 v[4:5], v[4:5], v[192:193]
	v_pk_mul_f32 v[30:31], v[30:31], v[158:159]
	v_pk_mul_f32 v[26:27], v[26:27], v[150:151]
	v_pk_mul_f32 v[22:23], v[22:23], v[146:147]
	v_pk_mul_f32 v[18:19], v[18:19], v[154:155]
	v_pk_mul_f32 v[16:17], v[16:17], v[152:153]
	v_pk_mul_f32 v[28:29], v[28:29], v[156:157]
	v_pk_mul_f32 v[24:25], v[24:25], v[148:149]
	v_pk_mul_f32 v[20:21], v[20:21], v[144:145]
	v_pk_mul_f32 v[62:63], v[62:63], v[126:127]
	v_pk_mul_f32 v[58:59], v[58:59], v[118:119]
	v_pk_mul_f32 v[54:55], v[54:55], v[114:115]
	v_pk_mul_f32 v[50:51], v[50:51], v[122:123]
	v_pk_mul_f32 v[48:49], v[48:49], v[120:121]
	v_pk_mul_f32 v[60:61], v[60:61], v[124:125]
	v_pk_mul_f32 v[56:57], v[56:57], v[116:117]
	v_pk_mul_f32 v[52:53], v[52:53], v[112:113]
	v_pk_mul_f32 v[46:47], v[46:47], v[110:111]
	v_pk_mul_f32 v[42:43], v[42:43], v[94:95]
	v_pk_mul_f32 v[38:39], v[38:39], v[86:87]
	v_pk_mul_f32 v[34:35], v[34:35], v[106:107]
	v_pk_mul_f32 v[32:33], v[32:33], v[104:105]
	v_pk_mul_f32 v[44:45], v[44:45], v[108:109]
	v_pk_mul_f32 v[40:41], v[40:41], v[92:93]
	v_pk_mul_f32 v[36:37], v[36:37], v[84:85]
	v_mfma_f32_32x32x16_bf16 v[0:15], v[188:191], v[80:83], v[0:15]
	s_lshl_b32 s8, s10, 2
	s_cmp_lg_u32 s3, 32
	s_cselect_b32 s76, s8, 0x80
	s_lshl_b64 s[8:9], s[76:77], 14
	s_lshl_b64 s[12:13], s[76:77], 9
	s_lshl_b64 s[14:15], s[76:77], 15
	s_cmp_eq_u32 s10, 33
	s_waitcnt vmcnt(3)
	v_mfma_f32_32x32x16_bf16 v[16:31], v[184:187], v[80:83], v[16:31]
	s_mov_b32 s3, s10
	v_mfma_f32_32x32x16_bf16 v[48:63], v[140:143], v[80:83], v[48:63]
	v_mfma_f32_32x32x16_bf16 v[32:47], v[100:103], v[80:83], v[32:47]
	v_lshl_add_u64 v[80:81], v[212:213], 0, s[14:15]
	v_mfma_f32_32x32x16_bf16 v[0:15], v[176:179], v[76:79], v[0:15]
	s_waitcnt vmcnt(2)
	v_mfma_f32_32x32x16_bf16 v[16:31], v[180:183], v[76:79], v[16:31]
	v_mfma_f32_32x32x16_bf16 v[48:63], v[136:139], v[76:79], v[48:63]
	v_mfma_f32_32x32x16_bf16 v[32:47], v[96:99], v[76:79], v[32:47]
	v_mfma_f32_32x32x16_bf16 v[0:15], v[164:167], v[72:75], v[0:15]
	s_waitcnt vmcnt(1)
	v_mfma_f32_32x32x16_bf16 v[16:31], v[172:175], v[72:75], v[16:31]
	v_mfma_f32_32x32x16_bf16 v[48:63], v[132:135], v[72:75], v[48:63]
	v_mfma_f32_32x32x16_bf16 v[32:47], v[88:91], v[72:75], v[32:47]
	v_lshl_add_u64 v[88:89], v[216:217], 0, s[12:13]
	v_mfma_f32_32x32x16_bf16 v[0:15], v[160:163], v[64:67], v[0:15]
	s_waitcnt vmcnt(0)
	v_mfma_f32_32x32x16_bf16 v[16:31], v[168:171], v[64:67], v[16:31]
	v_lshl_add_u64 v[168:169], v[214:215], 0, s[8:9]
	v_mfma_f32_32x32x16_bf16 v[48:63], v[128:131], v[64:67], v[48:63]
	v_mfma_f32_32x32x16_bf16 v[32:47], v[68:71], v[64:67], v[32:47]
	s_cbranch_scc1 .LBB0_79
; #define LAS __attribute__((address_space(3)))
; #define GLA_SPIN(cond) do { unsigned sp_ = 0; while ((cond) && ++sp_ < (1u << 22)) __builtin_amdgcn_s_sleep(1); } while (0)
; __device__ __forceinline__ void gla_seq_phase(const bf16* QDP, const bf16* KST, const bf16* ATT, const bf16* VT2, const float* DEC, float* OG, LAS unsigned char* lds, int tid, int wave, int lane, int G) {
;     ...
;         for (int n = 0; n < GLA_NCH; ++n) {
;             if (n >= 2) { GLA_SPIN(flags[1] < (unsigned)(n - 1) || flags[2] < (unsigned)(n - 1)); }
;             LAS unsigned char* slot = lds + (n & 1) * 8192 + lane * 16;
;             *(LAS bf16x8_t*)(slot + 0 * 1024) = gla_pack(S0, 0); *(LAS bf16x8_t*)(slot + 1 * 1024) = gla_pack(S0, 1); *(LAS bf16x8_t*)(slot + 2 * 1024) = gla_pack(S1, 0); *(LAS bf16x8_t*)(slot + 3 * 1024) = gla_pack(S1, 1);
;             *(LAS bf16x8_t*)(slot + 4 * 1024) = gla_pack(S2, 0); *(LAS bf16x8_t*)(slot + 5 * 1024) = gla_pack(S2, 1); *(LAS bf16x8_t*)(slot + 6 * 1024) = gla_pack(S3, 0); *(LAS bf16x8_t*)(slot + 7 * 1024) = gla_pack(S3, 1);
;             __builtin_amdgcn_fence(__ATOMIC_RELEASE, "workgroup");
;             if (lane == 0) flags[0] = (unsigned)(n + 1);
;             const int nn = n + 1 < GLA_NCH ? n + 1 : n;
;             const bf16* ksn = ksb + (size_t)nn * 4 * 8192; const float* decn = decb + (size_t)nn * 4 * 128; const bf16* vtn = vtb + (size_t)nn * 4 * 16384;
;     ...
;             GLA_SUPD(S0, k0, d0, 0); GLA_SUPD(S1, k1, d1, 1); GLA_SUPD(S2, k2, d2, 2); GLA_SUPD(S3, k3, d3, 3);
.LBB0_68:
	global_load_dwordx4 v[64:67], v[80:81], off offset:96
	global_load_dwordx4 v[72:75], v[80:81], off offset:64
	global_load_dwordx4 v[76:79], v[80:81], off offset:32
	s_nop 0
	global_load_dwordx4 v[80:83], v[80:81], off
	s_nop 0
	global_load_dwordx4 v[160:163], v[168:169], off offset:96
	global_load_dwordx4 v[164:167], v[168:169], off offset:64
	global_load_dwordx4 v[176:179], v[168:169], off offset:32
	global_load_dwordx4 v[188:191], v[168:169], off
	global_load_dwordx4 v[104:107], v[88:89], off offset:384
	global_load_dwordx4 v[84:87], v[88:89], off offset:416
	global_load_dwordx4 v[92:95], v[88:89], off offset:448
	global_load_dwordx4 v[108:111], v[88:89], off offset:480
	global_load_dwordx4 v[120:123], v[88:89], off offset:256
	global_load_dwordx4 v[112:115], v[88:89], off offset:288
	global_load_dwordx4 v[116:119], v[88:89], off offset:320
	global_load_dwordx4 v[124:127], v[88:89], off offset:352
	global_load_dwordx4 v[152:155], v[88:89], off offset:128
	global_load_dwordx4 v[144:147], v[88:89], off offset:160
	global_load_dwordx4 v[148:151], v[88:89], off offset:192
	global_load_dwordx4 v[156:159], v[88:89], off offset:224
	global_load_dwordx4 v[200:203], v[88:89], off
	global_load_dwordx4 v[192:195], v[88:89], off offset:32
	global_load_dwordx4 v[196:199], v[88:89], off offset:64
	global_load_dwordx4 v[204:207], v[88:89], off offset:96
	v_add_co_u32_e32 v68, vcc, 0x3000, v168
	s_cmp_lt_u32 s3, 2
	s_nop 0
	v_addc_co_u32_e32 v69, vcc, 0, v169, vcc
	v_add_co_u32_e32 v128, vcc, 0x2000, v168
	global_load_dwordx4 v[100:103], v[68:69], off
	global_load_dwordx4 v[96:99], v[68:69], off offset:32
	global_load_dwordx4 v[88:91], v[68:69], off offset:64
	s_nop 0
	global_load_dwordx4 v[68:71], v[68:69], off offset:96
	v_addc_co_u32_e32 v129, vcc, 0, v169, vcc
	v_add_co_u32_e32 v168, vcc, 0x1000, v168
	global_load_dwordx4 v[140:143], v[128:129], off
	global_load_dwordx4 v[136:139], v[128:129], off offset:32
	global_load_dwordx4 v[132:135], v[128:129], off offset:64
	s_nop 0
	global_load_dwordx4 v[128:131], v[128:129], off offset:96
	v_addc_co_u32_e32 v169, vcc, 0, v169, vcc
	global_load_dwordx4 v[184:187], v[168:169], off
	global_load_dwordx4 v[180:183], v[168:169], off offset:32
	global_load_dwordx4 v[172:175], v[168:169], off offset:64
	s_nop 0
	global_load_dwordx4 v[168:171], v[168:169], off offset:96
	s_cbranch_scc1 .LBB0_77
	s_add_i32 s12, s3, -1
	s_mov_b32 s13, 0x3fffff
	s_branch .LBB0_71

; __device__ __forceinline__ unsigned cvt_pk_bf16(float lo, float hi) { unsigned r; asm volatile("v_cvt_pk_bf16_f32 %0, %1, %2" : "=v"(r) : "v"(lo), "v"(hi)); return r; }
; __device__ __forceinline__ void row_rs8(const float* SS, int row0, int fq, float (&rs)[2][4]) {
;     f32x4 a[2][4];
; #pragma unroll
;     for (int ai = 0; ai < 2; ++ai)
; #pragma unroll
;         for (int m = 0; m < 4; ++m) a[ai][m] = *(const f32x4*)(SS + (size_t)(row0 + ai * HALF + m * 16) * 16 + 4 * fq);
; #pragma unroll
;     for (int ai = 0; ai < 2; ++ai)
; #pragma unroll
;         for (int m = 0; m < 4; ++m) { float s = (a[ai][m][0] + a[ai][m][1]) + (a[ai][m][2] + a[ai][m][3]); s += __shfl_xor(s, 16); s += xhalf(s, fq >= 2); rs[ai][m] = __builtin_amdgcn_rsqf(s * (1.0f / 1024.0f) + RMS_EPS); }
; }
; __device__ __forceinline__ float silu_f(float g) { return g * __builtin_amdgcn_rcpf(1.0f + __expf(-g)); }
;     __device__ __forceinline__ void operator()(const f32x4 (&acc)[2][2][4][2], const Unit& u, int wr, int wc, int fr, int fq) const {
;         const int row0 = u.pm * BM + wr * 64 + fr, col0 = u.pn * 128 + wc * 32 + 8 * fq;
;         float rs8[2][4]; row_rs8(SS, row0, fq, rs8);
; #pragma unroll
;         for (int ai = 0; ai < 2; ++ai)
; #pragma unroll
;             for (int m = 0; m < 4; ++m) {
;                 const int row = row0 + ai * HALF + m * 16; const float rs = rs8[ai][m];
;                 float o[8];
; #pragma unroll
;                 for (int n = 0; n < 2; ++n)
; #pragma unroll
;                     for (int j = 0; j < 4; ++j) { const float g = acc[ai][0][m][n][j] * rs, uu = acc[ai][1][m][n][j] * rs; o[4 * n + j] = silu_f(g) * uu; }
;                 u32x4 w; w.x = cvt_pk_bf16(o[0], o[1]); w.y = cvt_pk_bf16(o[2], o[3]); w.z = cvt_pk_bf16(o[4], o[5]); w.w = cvt_pk_bf16(o[6], o[7]);
;                 *(u32x4*)(ACT + (size_t)row * 2816 + col0) = w;
.LBB0_500:
	v_add_u32_e32 v152, s37, v169
	v_ashrrev_i32_e32 v153, 31, v152
	v_or_b32_e32 v148, 16, v152
	v_lshlrev_b64 v[128:129], 6, v[152:153]
	v_ashrrev_i32_e32 v149, 31, v148
	v_or_b32_e32 v144, 32, v152
	v_add_u32_e32 v132, 0x90, v152
	v_lshl_add_u64 v[128:129], v[176:177], 0, v[128:129]
	v_lshlrev_b64 v[130:131], 6, v[148:149]
	v_ashrrev_i32_e32 v145, 31, v144
	v_ashrrev_i32_e32 v133, 31, v132
	v_lshl_add_u64 v[130:131], v[176:177], 0, v[130:131]
	global_load_dwordx4 v[140:143], v[128:129], off
	global_load_dwordx4 v[156:159], v[130:131], off
	v_lshlrev_b64 v[128:129], 6, v[144:145]
	v_or_b32_e32 v138, 48, v152
	v_lshlrev_b64 v[136:137], 6, v[132:133]
	v_lshl_add_u64 v[128:129], v[176:177], 0, v[128:129]
	v_ashrrev_i32_e32 v139, 31, v138
	v_lshl_add_u64 v[136:137], v[176:177], 0, v[136:137]
	global_load_dwordx4 v[186:189], v[128:129], off
	global_load_dwordx4 v[198:201], v[136:137], off
	v_lshlrev_b64 v[128:129], 6, v[138:139]
	v_lshl_add_u64 v[128:129], v[176:177], 0, v[128:129]
	global_load_dwordx4 v[190:193], v[128:129], off
	v_add_u32_e32 v134, 0x80, v152
	v_ashrrev_i32_e32 v135, 31, v134
	v_lshlrev_b64 v[128:129], 6, v[134:135]
	v_lshl_add_u64 v[128:129], v[176:177], 0, v[128:129]
	global_load_dwordx4 v[194:197], v[128:129], off
	v_add_u32_e32 v130, 0xa0, v152
	v_and_b32_e32 v129, 64, v225
	v_add_u32_e32 v128, 0xb0, v152
	v_ashrrev_i32_e32 v131, 31, v130
	v_add_u32_e32 v139, 64, v129
	v_ashrrev_i32_e32 v129, 31, v128
	v_lshlrev_b64 v[136:137], 6, v[130:131]
	v_lshlrev_b64 v[146:147], 6, v[128:129]
	v_lshl_add_u64 v[136:137], v[176:177], 0, v[136:137]
	v_lshl_add_u64 v[146:147], v[176:177], 0, v[146:147]
	global_load_dwordx4 v[202:205], v[136:137], off
	global_load_dwordx4 v[214:217], v[146:147], off
	v_xor_b32_e32 v135, 16, v225
	v_cmp_lt_i32_e32 vcc, v135, v139
	v_lshl_or_b32 v154, s44, 7, v207
	v_ashrrev_i32_e32 v155, 31, v154
	v_cndmask_b32_e32 v133, v225, v135, vcc
	v_lshlrev_b32_e32 v129, 2, v133
	s_waitcnt vmcnt(0)
	v_add_f32_e32 v140, v140, v141
	v_add_f32_e32 v142, v142, v143
	v_add_f32_e32 v156, v156, v157
	v_add_f32_e32 v158, v158, v159
	v_add_f32_e32 v186, v186, v187
	v_add_f32_e32 v188, v188, v189
	v_add_f32_e32 v190, v190, v191
	v_add_f32_e32 v192, v192, v193
	v_add_f32_e32 v194, v194, v195
	v_add_f32_e32 v196, v196, v197
	v_add_f32_e32 v198, v198, v199
	v_add_f32_e32 v200, v200, v201
	v_add_f32_e32 v202, v202, v203
	v_add_f32_e32 v204, v204, v205
	v_add_f32_e32 v214, v214, v215
	v_add_f32_e32 v216, v216, v217
	v_add_f32_e32 v140, v140, v142
	v_add_f32_e32 v156, v156, v158
	v_add_f32_e32 v186, v186, v188
	v_add_f32_e32 v190, v190, v192
	v_add_f32_e32 v194, v194, v196
	v_add_f32_e32 v198, v198, v200
	v_add_f32_e32 v202, v202, v204
	v_add_f32_e32 v214, v214, v216
	ds_bpermute_b32 v143, v129, v140
	ds_bpermute_b32 v159, v129, v156
	ds_bpermute_b32 v189, v129, v186
	ds_bpermute_b32 v193, v129, v190
	ds_bpermute_b32 v197, v129, v194
	ds_bpermute_b32 v201, v129, v198
	ds_bpermute_b32 v205, v129, v202
	ds_bpermute_b32 v217, v129, v214
	v_mov_b64_e32 v[226:227], s[26:27]
	v_lshlrev_b64 v[228:229], 1, v[154:155]
	s_waitcnt lgkmcnt(0)
	v_add_f32_e32 v140, v140, v143
	v_add_f32_e32 v156, v156, v159
	v_add_f32_e32 v186, v186, v189
	v_add_f32_e32 v190, v190, v193
	v_add_f32_e32 v194, v194, v197
	v_add_f32_e32 v198, v198, v201
	v_add_f32_e32 v202, v202, v205
	v_add_f32_e32 v214, v214, v217
	v_mov_b32_e32 v141, v140
	v_mov_b32_e32 v142, v140
	v_mov_b32_e32 v157, v156
	v_mov_b32_e32 v158, v156
	v_mov_b32_e32 v187, v186
	v_mov_b32_e32 v188, v186
	v_mov_b32_e32 v191, v190
	v_mov_b32_e32 v192, v190
	v_mov_b32_e32 v195, v194
	v_mov_b32_e32 v196, v194
	v_mov_b32_e32 v199, v198
	v_mov_b32_e32 v200, v198
	v_mov_b32_e32 v203, v202
	v_mov_b32_e32 v204, v202
	v_mov_b32_e32 v215, v214
	v_mov_b32_e32 v216, v214
	s_nop 1
	v_permlane32_swap_b32_e32 v141, v142
	v_permlane32_swap_b32_e32 v157, v158
	v_permlane32_swap_b32_e32 v187, v188
	v_permlane32_swap_b32_e32 v191, v192
	v_permlane32_swap_b32_e32 v195, v196
	v_permlane32_swap_b32_e32 v199, v200
	v_permlane32_swap_b32_e32 v203, v204
	v_permlane32_swap_b32_e32 v215, v216
	v_cndmask_b32_e64 v141, v142, v141, s[6:7]
	v_cndmask_b32_e64 v157, v158, v157, s[6:7]
	v_cndmask_b32_e64 v187, v188, v187, s[6:7]
	v_cndmask_b32_e64 v191, v192, v191, s[6:7]
	v_cndmask_b32_e64 v195, v196, v195, s[6:7]
	v_cndmask_b32_e64 v199, v200, v199, s[6:7]
	v_cndmask_b32_e64 v203, v204, v203, s[6:7]
	v_cndmask_b32_e64 v215, v216, v215, s[6:7]
	v_add_f32_e32 v140, v140, v141
	v_add_f32_e32 v156, v156, v157
	v_add_f32_e32 v186, v186, v187
	v_add_f32_e32 v190, v190, v191
	v_add_f32_e32 v194, v194, v195
	v_add_f32_e32 v198, v198, v199
	v_add_f32_e32 v202, v202, v203
	v_add_f32_e32 v214, v214, v215
	v_fmamk_f32 v140, v140, 0x3a800000, v209
	v_fmamk_f32 v156, v156, 0x3a800000, v209
	v_fmamk_f32 v186, v186, 0x3a800000, v209
	v_fmamk_f32 v190, v190, 0x3a800000, v209
	v_fmamk_f32 v194, v194, 0x3a800000, v209
	v_fmamk_f32 v198, v198, 0x3a800000, v209
	v_fmamk_f32 v202, v202, 0x3a800000, v209
	v_fmamk_f32 v214, v214, 0x3a800000, v209
	v_rsq_f32_e32 v140, v140
	v_rsq_f32_e32 v156, v156
	v_rsq_f32_e32 v186, v186
	v_rsq_f32_e32 v190, v190
	v_rsq_f32_e32 v194, v194
	v_rsq_f32_e32 v198, v198
	v_rsq_f32_e32 v202, v202
	v_rsq_f32_e32 v214, v214
	v_mov_b32_e32 v216, 0xbfb8aa3b
	v_mov_b32_e32 v204, 1.0
	v_pk_mul_f32 v[124:125], v[124:125], v[140:141] op_sel_hi:[1,0]
	v_pk_mul_f32 v[126:127], v[126:127], v[140:141] op_sel_hi:[1,0]
	v_pk_mul_f32 v[116:117], v[116:117], v[140:141] op_sel_hi:[1,0]
	v_pk_mul_f32 v[118:119], v[118:119], v[140:141] op_sel_hi:[1,0]
	v_pk_mul_f32 v[142:143], v[124:125], v[216:217] op_sel_hi:[1,0]
; __device__ __forceinline__ unsigned cvt_pk_bf16(float lo, float hi) { unsigned r; asm volatile("v_cvt_pk_bf16_f32 %0, %1, %2" : "=v"(r) : "v"(lo), "v"(hi)); return r; }
; __device__ __forceinline__ float silu_f(float g) { return g * __builtin_amdgcn_rcpf(1.0f + __expf(-g)); }
;     __device__ __forceinline__ void operator()(const f32x4 (&acc)[2][2][4][2], const Unit& u, int wr, int wc, int fr, int fq) const {
;         const int row0 = u.pm * BM + wr * 64 + fr, col0 = u.pn * 128 + wc * 32 + 8 * fq;
;         float rs8[2][4]; row_rs8(SS, row0, fq, rs8);
; #pragma unroll
;         for (int ai = 0; ai < 2; ++ai)
; #pragma unroll
;             for (int m = 0; m < 4; ++m) {
;                 const int row = row0 + ai * HALF + m * 16; const float rs = rs8[ai][m];
;                 float o[8];
; #pragma unroll
;                 for (int n = 0; n < 2; ++n)
; #pragma unroll
;                     for (int j = 0; j < 4; ++j) { const float g = acc[ai][0][m][n][j] * rs, uu = acc[ai][1][m][n][j] * rs; o[4 * n + j] = silu_f(g) * uu; }
;                 u32x4 w; w.x = cvt_pk_bf16(o[0], o[1]); w.y = cvt_pk_bf16(o[2], o[3]); w.z = cvt_pk_bf16(o[4], o[5]); w.w = cvt_pk_bf16(o[6], o[7]);
;                 *(u32x4*)(ACT + (size_t)row * 2816 + col0) = w;
;                 asm volatile("" ::: "memory");
;             }
	v_pk_mul_f32 v[158:159], v[126:127], v[216:217] op_sel_hi:[1,0]
	v_pk_mul_f32 v[188:189], v[116:117], v[216:217] op_sel_hi:[1,0]
	v_pk_mul_f32 v[192:193], v[118:119], v[216:217] op_sel_hi:[1,0]
	v_exp_f32_e32 v142, v142
	v_exp_f32_e32 v143, v143
	v_exp_f32_e32 v158, v158
	v_exp_f32_e32 v159, v159
	v_exp_f32_e32 v188, v188
	v_exp_f32_e32 v189, v189
	v_exp_f32_e32 v192, v192
	v_exp_f32_e32 v193, v193
	v_pk_mul_f32 v[120:121], v[120:121], v[140:141] op_sel_hi:[1,0]
	v_pk_mul_f32 v[122:123], v[122:123], v[140:141] op_sel_hi:[1,0]
	v_pk_mul_f32 v[112:113], v[112:113], v[140:141] op_sel_hi:[1,0]
	v_pk_mul_f32 v[114:115], v[114:115], v[140:141] op_sel_hi:[1,0]
	v_pk_add_f32 v[142:143], v[142:143], v[204:205] op_sel_hi:[1,0]
	v_pk_add_f32 v[158:159], v[158:159], v[204:205] op_sel_hi:[1,0]
	v_pk_add_f32 v[188:189], v[188:189], v[204:205] op_sel_hi:[1,0]
	v_pk_add_f32 v[192:193], v[192:193], v[204:205] op_sel_hi:[1,0]
	v_rcp_f32_e32 v142, v142
	v_rcp_f32_e32 v143, v143
	v_rcp_f32_e32 v158, v158
	v_rcp_f32_e32 v159, v159
	v_rcp_f32_e32 v188, v188
	v_rcp_f32_e32 v189, v189
	v_rcp_f32_e32 v192, v192
	v_rcp_f32_e32 v193, v193
	v_mad_i64_i32 v[230:231], s[10:11], v152, s53, v[226:227]
	v_lshl_add_u64 v[230:231], v[230:231], 0, v[228:229]
	v_pk_mul_f32 v[142:143], v[124:125], v[142:143]
	v_pk_mul_f32 v[158:159], v[126:127], v[158:159]
	v_pk_mul_f32 v[188:189], v[116:117], v[188:189]
	v_pk_mul_f32 v[192:193], v[118:119], v[192:193]
	v_pk_mul_f32 v[120:121], v[120:121], v[142:143]
	v_pk_mul_f32 v[122:123], v[122:123], v[158:159]
	v_pk_mul_f32 v[112:113], v[112:113], v[188:189]
	v_pk_mul_f32 v[114:115], v[114:115], v[192:193]
	v_cvt_pk_bf16_f32 v232, v120, v121
	v_cvt_pk_bf16_f32 v233, v122, v123
	v_cvt_pk_bf16_f32 v234, v112, v113
	v_cvt_pk_bf16_f32 v235, v114, v115
	global_store_dwordx4 v[230:231], v[232:235], off
	v_pk_mul_f32 v[108:109], v[108:109], v[156:157] op_sel_hi:[1,0]
	v_pk_mul_f32 v[110:111], v[110:111], v[156:157] op_sel_hi:[1,0]
	v_pk_mul_f32 v[100:101], v[100:101], v[156:157] op_sel_hi:[1,0]
	v_pk_mul_f32 v[102:103], v[102:103], v[156:157] op_sel_hi:[1,0]
	v_pk_mul_f32 v[142:143], v[108:109], v[216:217] op_sel_hi:[1,0]
	v_pk_mul_f32 v[158:159], v[110:111], v[216:217] op_sel_hi:[1,0]
	v_pk_mul_f32 v[188:189], v[100:101], v[216:217] op_sel_hi:[1,0]
	v_pk_mul_f32 v[192:193], v[102:103], v[216:217] op_sel_hi:[1,0]
	v_exp_f32_e32 v142, v142
	v_exp_f32_e32 v143, v143
	v_exp_f32_e32 v158, v158
	v_exp_f32_e32 v159, v159
	v_exp_f32_e32 v188, v188
	v_exp_f32_e32 v189, v189
	v_exp_f32_e32 v192, v192
	v_exp_f32_e32 v193, v193
	v_pk_mul_f32 v[104:105], v[104:105], v[156:157] op_sel_hi:[1,0]
	v_pk_mul_f32 v[106:107], v[106:107], v[156:157] op_sel_hi:[1,0]
	v_pk_mul_f32 v[96:97], v[96:97], v[156:157] op_sel_hi:[1,0]
	v_pk_mul_f32 v[98:99], v[98:99], v[156:157] op_sel_hi:[1,0]
	v_pk_add_f32 v[142:143], v[142:143], v[204:205] op_sel_hi:[1,0]
	v_pk_add_f32 v[158:159], v[158:159], v[204:205] op_sel_hi:[1,0]
	v_pk_add_f32 v[188:189], v[188:189], v[204:205] op_sel_hi:[1,0]
	v_pk_add_f32 v[192:193], v[192:193], v[204:205] op_sel_hi:[1,0]
	v_rcp_f32_e32 v142, v142
	v_rcp_f32_e32 v143, v143
	v_rcp_f32_e32 v158, v158
	v_rcp_f32_e32 v159, v159
	v_rcp_f32_e32 v188, v188
	v_rcp_f32_e32 v189, v189
	v_rcp_f32_e32 v192, v192
	v_rcp_f32_e32 v193, v193
	v_mad_i64_i32 v[230:231], s[10:11], v148, s53, v[226:227]
	v_lshl_add_u64 v[230:231], v[230:231], 0, v[228:229]
	v_pk_mul_f32 v[142:143], v[108:109], v[142:143]
	v_pk_mul_f32 v[158:159], v[110:111], v[158:159]
	v_pk_mul_f32 v[188:189], v[100:101], v[188:189]
	v_pk_mul_f32 v[192:193], v[102:103], v[192:193]
	v_pk_mul_f32 v[104:105], v[104:105], v[142:143]
	v_pk_mul_f32 v[106:107], v[106:107], v[158:159]
	v_pk_mul_f32 v[96:97], v[96:97], v[188:189]
	v_pk_mul_f32 v[98:99], v[98:99], v[192:193]
	v_cvt_pk_bf16_f32 v232, v104, v105
	v_cvt_pk_bf16_f32 v233, v106, v107
	v_cvt_pk_bf16_f32 v234, v96, v97
	v_cvt_pk_bf16_f32 v235, v98, v99
	global_store_dwordx4 v[230:231], v[232:235], off
	v_pk_mul_f32 v[92:93], v[92:93], v[186:187] op_sel_hi:[1,0]
	v_pk_mul_f32 v[94:95], v[94:95], v[186:187] op_sel_hi:[1,0]
	v_pk_mul_f32 v[84:85], v[84:85], v[186:187] op_sel_hi:[1,0]
	v_pk_mul_f32 v[86:87], v[86:87], v[186:187] op_sel_hi:[1,0]
	v_pk_mul_f32 v[142:143], v[92:93], v[216:217] op_sel_hi:[1,0]
	v_pk_mul_f32 v[158:159], v[94:95], v[216:217] op_sel_hi:[1,0]
	v_pk_mul_f32 v[188:189], v[84:85], v[216:217] op_sel_hi:[1,0]
	v_pk_mul_f32 v[192:193], v[86:87], v[216:217] op_sel_hi:[1,0]
	v_exp_f32_e32 v142, v142
	v_exp_f32_e32 v143, v143
	v_exp_f32_e32 v158, v158
	v_exp_f32_e32 v159, v159
	v_exp_f32_e32 v188, v188
	v_exp_f32_e32 v189, v189
	v_exp_f32_e32 v192, v192
	v_exp_f32_e32 v193, v193
	v_pk_mul_f32 v[88:89], v[88:89], v[186:187] op_sel_hi:[1,0]
	v_pk_mul_f32 v[90:91], v[90:91], v[186:187] op_sel_hi:[1,0]
	v_pk_mul_f32 v[80:81], v[80:81], v[186:187] op_sel_hi:[1,0]
	v_pk_mul_f32 v[82:83], v[82:83], v[186:187] op_sel_hi:[1,0]
	v_pk_add_f32 v[142:143], v[142:143], v[204:205] op_sel_hi:[1,0]
	v_pk_add_f32 v[158:159], v[158:159], v[204:205] op_sel_hi:[1,0]
	v_pk_add_f32 v[188:189], v[188:189], v[204:205] op_sel_hi:[1,0]
	v_pk_add_f32 v[192:193], v[192:193], v[204:205] op_sel_hi:[1,0]
	v_rcp_f32_e32 v142, v142
	v_rcp_f32_e32 v143, v143
	v_rcp_f32_e32 v158, v158
	v_rcp_f32_e32 v159, v159
	v_rcp_f32_e32 v188, v188
	v_rcp_f32_e32 v189, v189
	v_rcp_f32_e32 v192, v192
	v_rcp_f32_e32 v193, v193
	v_mad_i64_i32 v[230:231], s[10:11], v144, s53, v[226:227]
	v_lshl_add_u64 v[230:231], v[230:231], 0, v[228:229]
	v_pk_mul_f32 v[142:143], v[92:93], v[142:143]
	v_pk_mul_f32 v[158:159], v[94:95], v[158:159]
	v_pk_mul_f32 v[188:189], v[84:85], v[188:189]
; __device__ __forceinline__ unsigned cvt_pk_bf16(float lo, float hi) { unsigned r; asm volatile("v_cvt_pk_bf16_f32 %0, %1, %2" : "=v"(r) : "v"(lo), "v"(hi)); return r; }
; __device__ __forceinline__ float silu_f(float g) { return g * __builtin_amdgcn_rcpf(1.0f + __expf(-g)); }
;     __device__ __forceinline__ void operator()(const f32x4 (&acc)[2][2][4][2], const Unit& u, int wr, int wc, int fr, int fq) const {
;         const int row0 = u.pm * BM + wr * 64 + fr, col0 = u.pn * 128 + wc * 32 + 8 * fq;
;         float rs8[2][4]; row_rs8(SS, row0, fq, rs8);
; #pragma unroll
;         for (int ai = 0; ai < 2; ++ai)
; #pragma unroll
;             for (int m = 0; m < 4; ++m) {
;                 const int row = row0 + ai * HALF + m * 16; const float rs = rs8[ai][m];
;                 float o[8];
; #pragma unroll
;                 for (int n = 0; n < 2; ++n)
; #pragma unroll
;                     for (int j = 0; j < 4; ++j) { const float g = acc[ai][0][m][n][j] * rs, uu = acc[ai][1][m][n][j] * rs; o[4 * n + j] = silu_f(g) * uu; }
;                 u32x4 w; w.x = cvt_pk_bf16(o[0], o[1]); w.y = cvt_pk_bf16(o[2], o[3]); w.z = cvt_pk_bf16(o[4], o[5]); w.w = cvt_pk_bf16(o[6], o[7]);
;                 *(u32x4*)(ACT + (size_t)row * 2816 + col0) = w;
;                 asm volatile("" ::: "memory");
;             }
	v_pk_mul_f32 v[192:193], v[86:87], v[192:193]
	v_pk_mul_f32 v[88:89], v[88:89], v[142:143]
	v_pk_mul_f32 v[90:91], v[90:91], v[158:159]
	v_pk_mul_f32 v[80:81], v[80:81], v[188:189]
	v_pk_mul_f32 v[82:83], v[82:83], v[192:193]
	v_cvt_pk_bf16_f32 v232, v88, v89
	v_cvt_pk_bf16_f32 v233, v90, v91
	v_cvt_pk_bf16_f32 v234, v80, v81
	v_cvt_pk_bf16_f32 v235, v82, v83
	global_store_dwordx4 v[230:231], v[232:235], off
	v_pk_mul_f32 v[76:77], v[76:77], v[190:191] op_sel_hi:[1,0]
	v_pk_mul_f32 v[78:79], v[78:79], v[190:191] op_sel_hi:[1,0]
	v_pk_mul_f32 v[68:69], v[68:69], v[190:191] op_sel_hi:[1,0]
	v_pk_mul_f32 v[70:71], v[70:71], v[190:191] op_sel_hi:[1,0]
	v_pk_mul_f32 v[142:143], v[76:77], v[216:217] op_sel_hi:[1,0]
	v_pk_mul_f32 v[158:159], v[78:79], v[216:217] op_sel_hi:[1,0]
	v_pk_mul_f32 v[188:189], v[68:69], v[216:217] op_sel_hi:[1,0]
	v_pk_mul_f32 v[192:193], v[70:71], v[216:217] op_sel_hi:[1,0]
	v_exp_f32_e32 v142, v142
	v_exp_f32_e32 v143, v143
	v_exp_f32_e32 v158, v158
	v_exp_f32_e32 v159, v159
	v_exp_f32_e32 v188, v188
	v_exp_f32_e32 v189, v189
	v_exp_f32_e32 v192, v192
	v_exp_f32_e32 v193, v193
	v_pk_mul_f32 v[72:73], v[72:73], v[190:191] op_sel_hi:[1,0]
	v_pk_mul_f32 v[74:75], v[74:75], v[190:191] op_sel_hi:[1,0]
	v_pk_mul_f32 v[64:65], v[64:65], v[190:191] op_sel_hi:[1,0]
	v_pk_mul_f32 v[66:67], v[66:67], v[190:191] op_sel_hi:[1,0]
	v_pk_add_f32 v[142:143], v[142:143], v[204:205] op_sel_hi:[1,0]
	v_pk_add_f32 v[158:159], v[158:159], v[204:205] op_sel_hi:[1,0]
	v_pk_add_f32 v[188:189], v[188:189], v[204:205] op_sel_hi:[1,0]
	v_pk_add_f32 v[192:193], v[192:193], v[204:205] op_sel_hi:[1,0]
	v_rcp_f32_e32 v142, v142
	v_rcp_f32_e32 v143, v143
	v_rcp_f32_e32 v158, v158
	v_rcp_f32_e32 v159, v159
	v_rcp_f32_e32 v188, v188
	v_rcp_f32_e32 v189, v189
	v_rcp_f32_e32 v192, v192
	v_rcp_f32_e32 v193, v193
	v_mad_i64_i32 v[230:231], s[10:11], v138, s53, v[226:227]
	v_lshl_add_u64 v[230:231], v[230:231], 0, v[228:229]
	v_pk_mul_f32 v[142:143], v[76:77], v[142:143]
	v_pk_mul_f32 v[158:159], v[78:79], v[158:159]
	v_pk_mul_f32 v[188:189], v[68:69], v[188:189]
	v_pk_mul_f32 v[192:193], v[70:71], v[192:193]
	v_pk_mul_f32 v[72:73], v[72:73], v[142:143]
	v_pk_mul_f32 v[74:75], v[74:75], v[158:159]
	v_pk_mul_f32 v[64:65], v[64:65], v[188:189]
	v_pk_mul_f32 v[66:67], v[66:67], v[192:193]
	v_cvt_pk_bf16_f32 v232, v72, v73
	v_cvt_pk_bf16_f32 v233, v74, v75
	v_cvt_pk_bf16_f32 v234, v64, v65
	v_cvt_pk_bf16_f32 v235, v66, v67
	global_store_dwordx4 v[230:231], v[232:235], off
	v_pk_mul_f32 v[60:61], v[60:61], v[194:195] op_sel_hi:[1,0]
	v_pk_mul_f32 v[62:63], v[62:63], v[194:195] op_sel_hi:[1,0]
	v_pk_mul_f32 v[52:53], v[52:53], v[194:195] op_sel_hi:[1,0]
	v_pk_mul_f32 v[54:55], v[54:55], v[194:195] op_sel_hi:[1,0]
	v_pk_mul_f32 v[142:143], v[60:61], v[216:217] op_sel_hi:[1,0]
	v_pk_mul_f32 v[158:159], v[62:63], v[216:217] op_sel_hi:[1,0]
	v_pk_mul_f32 v[188:189], v[52:53], v[216:217] op_sel_hi:[1,0]
	v_pk_mul_f32 v[192:193], v[54:55], v[216:217] op_sel_hi:[1,0]
	v_exp_f32_e32 v142, v142
	v_exp_f32_e32 v143, v143
	v_exp_f32_e32 v158, v158
	v_exp_f32_e32 v159, v159
	v_exp_f32_e32 v188, v188
	v_exp_f32_e32 v189, v189
	v_exp_f32_e32 v192, v192
	v_exp_f32_e32 v193, v193
	v_pk_mul_f32 v[56:57], v[56:57], v[194:195] op_sel_hi:[1,0]
	v_pk_mul_f32 v[58:59], v[58:59], v[194:195] op_sel_hi:[1,0]
	v_pk_mul_f32 v[48:49], v[48:49], v[194:195] op_sel_hi:[1,0]
	v_pk_mul_f32 v[50:51], v[50:51], v[194:195] op_sel_hi:[1,0]
	v_pk_add_f32 v[142:143], v[142:143], v[204:205] op_sel_hi:[1,0]
	v_pk_add_f32 v[158:159], v[158:159], v[204:205] op_sel_hi:[1,0]
	v_pk_add_f32 v[188:189], v[188:189], v[204:205] op_sel_hi:[1,0]
	v_pk_add_f32 v[192:193], v[192:193], v[204:205] op_sel_hi:[1,0]
	v_rcp_f32_e32 v142, v142
	v_rcp_f32_e32 v143, v143
	v_rcp_f32_e32 v158, v158
	v_rcp_f32_e32 v159, v159
	v_rcp_f32_e32 v188, v188
	v_rcp_f32_e32 v189, v189
	v_rcp_f32_e32 v192, v192
	v_rcp_f32_e32 v193, v193
	v_mad_i64_i32 v[230:231], s[10:11], v134, s53, v[226:227]
	v_lshl_add_u64 v[230:231], v[230:231], 0, v[228:229]
	v_pk_mul_f32 v[142:143], v[60:61], v[142:143]
	v_pk_mul_f32 v[158:159], v[62:63], v[158:159]
	v_pk_mul_f32 v[188:189], v[52:53], v[188:189]
	v_pk_mul_f32 v[192:193], v[54:55], v[192:193]
	v_pk_mul_f32 v[56:57], v[56:57], v[142:143]
	v_pk_mul_f32 v[58:59], v[58:59], v[158:159]
	v_pk_mul_f32 v[48:49], v[48:49], v[188:189]
	v_pk_mul_f32 v[50:51], v[50:51], v[192:193]
	v_cvt_pk_bf16_f32 v232, v56, v57
	v_cvt_pk_bf16_f32 v233, v58, v59
	v_cvt_pk_bf16_f32 v234, v48, v49
	v_cvt_pk_bf16_f32 v235, v50, v51
	global_store_dwordx4 v[230:231], v[232:235], off
	v_pk_mul_f32 v[44:45], v[44:45], v[198:199] op_sel_hi:[1,0]
	v_pk_mul_f32 v[46:47], v[46:47], v[198:199] op_sel_hi:[1,0]
	v_pk_mul_f32 v[36:37], v[36:37], v[198:199] op_sel_hi:[1,0]
	v_pk_mul_f32 v[38:39], v[38:39], v[198:199] op_sel_hi:[1,0]
	v_pk_mul_f32 v[142:143], v[44:45], v[216:217] op_sel_hi:[1,0]
	v_pk_mul_f32 v[158:159], v[46:47], v[216:217] op_sel_hi:[1,0]
	v_pk_mul_f32 v[188:189], v[36:37], v[216:217] op_sel_hi:[1,0]
	v_pk_mul_f32 v[192:193], v[38:39], v[216:217] op_sel_hi:[1,0]
	v_exp_f32_e32 v142, v142
	v_exp_f32_e32 v143, v143
	v_exp_f32_e32 v158, v158
	v_exp_f32_e32 v159, v159
	v_exp_f32_e32 v188, v188
	v_exp_f32_e32 v189, v189
	v_exp_f32_e32 v192, v192
	v_exp_f32_e32 v193, v193
	v_pk_mul_f32 v[40:41], v[40:41], v[198:199] op_sel_hi:[1,0]
	v_pk_mul_f32 v[42:43], v[42:43], v[198:199] op_sel_hi:[1,0]
	v_pk_mul_f32 v[32:33], v[32:33], v[198:199] op_sel_hi:[1,0]
; __device__ __forceinline__ unsigned cvt_pk_bf16(float lo, float hi) { unsigned r; asm volatile("v_cvt_pk_bf16_f32 %0, %1, %2" : "=v"(r) : "v"(lo), "v"(hi)); return r; }
; __device__ __forceinline__ float silu_f(float g) { return g * __builtin_amdgcn_rcpf(1.0f + __expf(-g)); }
;     __device__ __forceinline__ void operator()(const f32x4 (&acc)[2][2][4][2], const Unit& u, int wr, int wc, int fr, int fq) const {
;         const int row0 = u.pm * BM + wr * 64 + fr, col0 = u.pn * 128 + wc * 32 + 8 * fq;
;         float rs8[2][4]; row_rs8(SS, row0, fq, rs8);
; #pragma unroll
;         for (int ai = 0; ai < 2; ++ai)
; #pragma unroll
;             for (int m = 0; m < 4; ++m) {
;                 const int row = row0 + ai * HALF + m * 16; const float rs = rs8[ai][m];
;                 float o[8];
; #pragma unroll
;                 for (int n = 0; n < 2; ++n)
; #pragma unroll
;                     for (int j = 0; j < 4; ++j) { const float g = acc[ai][0][m][n][j] * rs, uu = acc[ai][1][m][n][j] * rs; o[4 * n + j] = silu_f(g) * uu; }
;                 u32x4 w; w.x = cvt_pk_bf16(o[0], o[1]); w.y = cvt_pk_bf16(o[2], o[3]); w.z = cvt_pk_bf16(o[4], o[5]); w.w = cvt_pk_bf16(o[6], o[7]);
;                 *(u32x4*)(ACT + (size_t)row * 2816 + col0) = w;
;                 asm volatile("" ::: "memory");
;             }
	v_pk_mul_f32 v[34:35], v[34:35], v[198:199] op_sel_hi:[1,0]
	v_pk_add_f32 v[142:143], v[142:143], v[204:205] op_sel_hi:[1,0]
	v_pk_add_f32 v[158:159], v[158:159], v[204:205] op_sel_hi:[1,0]
	v_pk_add_f32 v[188:189], v[188:189], v[204:205] op_sel_hi:[1,0]
	v_pk_add_f32 v[192:193], v[192:193], v[204:205] op_sel_hi:[1,0]
	v_rcp_f32_e32 v142, v142
	v_rcp_f32_e32 v143, v143
	v_rcp_f32_e32 v158, v158
	v_rcp_f32_e32 v159, v159
	v_rcp_f32_e32 v188, v188
	v_rcp_f32_e32 v189, v189
	v_rcp_f32_e32 v192, v192
	v_rcp_f32_e32 v193, v193
	v_mad_i64_i32 v[230:231], s[10:11], v132, s53, v[226:227]
	v_lshl_add_u64 v[230:231], v[230:231], 0, v[228:229]
	v_pk_mul_f32 v[142:143], v[44:45], v[142:143]
	v_pk_mul_f32 v[158:159], v[46:47], v[158:159]
	v_pk_mul_f32 v[188:189], v[36:37], v[188:189]
	v_pk_mul_f32 v[192:193], v[38:39], v[192:193]
	v_pk_mul_f32 v[40:41], v[40:41], v[142:143]
	v_pk_mul_f32 v[42:43], v[42:43], v[158:159]
	v_pk_mul_f32 v[32:33], v[32:33], v[188:189]
	v_pk_mul_f32 v[34:35], v[34:35], v[192:193]
	v_cvt_pk_bf16_f32 v232, v40, v41
	v_cvt_pk_bf16_f32 v233, v42, v43
	v_cvt_pk_bf16_f32 v234, v32, v33
	v_cvt_pk_bf16_f32 v235, v34, v35
	global_store_dwordx4 v[230:231], v[232:235], off
	v_pk_mul_f32 v[28:29], v[28:29], v[202:203] op_sel_hi:[1,0]
	v_pk_mul_f32 v[30:31], v[30:31], v[202:203] op_sel_hi:[1,0]
	v_pk_mul_f32 v[20:21], v[20:21], v[202:203] op_sel_hi:[1,0]
	v_pk_mul_f32 v[22:23], v[22:23], v[202:203] op_sel_hi:[1,0]
	v_pk_mul_f32 v[142:143], v[28:29], v[216:217] op_sel_hi:[1,0]
	v_pk_mul_f32 v[158:159], v[30:31], v[216:217] op_sel_hi:[1,0]
	v_pk_mul_f32 v[188:189], v[20:21], v[216:217] op_sel_hi:[1,0]
	v_pk_mul_f32 v[192:193], v[22:23], v[216:217] op_sel_hi:[1,0]
	v_exp_f32_e32 v142, v142
	v_exp_f32_e32 v143, v143
	v_exp_f32_e32 v158, v158
	v_exp_f32_e32 v159, v159
	v_exp_f32_e32 v188, v188
	v_exp_f32_e32 v189, v189
	v_exp_f32_e32 v192, v192
	v_exp_f32_e32 v193, v193
	v_pk_mul_f32 v[24:25], v[24:25], v[202:203] op_sel_hi:[1,0]
	v_pk_mul_f32 v[26:27], v[26:27], v[202:203] op_sel_hi:[1,0]
	v_pk_mul_f32 v[16:17], v[16:17], v[202:203] op_sel_hi:[1,0]
	v_pk_mul_f32 v[18:19], v[18:19], v[202:203] op_sel_hi:[1,0]
	v_pk_add_f32 v[142:143], v[142:143], v[204:205] op_sel_hi:[1,0]
	v_pk_add_f32 v[158:159], v[158:159], v[204:205] op_sel_hi:[1,0]
	v_pk_add_f32 v[188:189], v[188:189], v[204:205] op_sel_hi:[1,0]
	v_pk_add_f32 v[192:193], v[192:193], v[204:205] op_sel_hi:[1,0]
	v_rcp_f32_e32 v142, v142
	v_rcp_f32_e32 v143, v143
	v_rcp_f32_e32 v158, v158
	v_rcp_f32_e32 v159, v159
	v_rcp_f32_e32 v188, v188
	v_rcp_f32_e32 v189, v189
	v_rcp_f32_e32 v192, v192
	v_rcp_f32_e32 v193, v193
	v_mad_i64_i32 v[230:231], s[10:11], v130, s53, v[226:227]
	v_lshl_add_u64 v[230:231], v[230:231], 0, v[228:229]
	v_pk_mul_f32 v[142:143], v[28:29], v[142:143]
	v_pk_mul_f32 v[158:159], v[30:31], v[158:159]
	v_pk_mul_f32 v[188:189], v[20:21], v[188:189]
	v_pk_mul_f32 v[192:193], v[22:23], v[192:193]
	v_pk_mul_f32 v[24:25], v[24:25], v[142:143]
	v_pk_mul_f32 v[26:27], v[26:27], v[158:159]
	v_pk_mul_f32 v[16:17], v[16:17], v[188:189]
	v_pk_mul_f32 v[18:19], v[18:19], v[192:193]
	v_cvt_pk_bf16_f32 v232, v24, v25
	v_cvt_pk_bf16_f32 v233, v26, v27
	v_cvt_pk_bf16_f32 v234, v16, v17
	v_cvt_pk_bf16_f32 v235, v18, v19
	global_store_dwordx4 v[230:231], v[232:235], off
	v_pk_mul_f32 v[12:13], v[12:13], v[214:215] op_sel_hi:[1,0]
	v_pk_mul_f32 v[14:15], v[14:15], v[214:215] op_sel_hi:[1,0]
	v_pk_mul_f32 v[4:5], v[4:5], v[214:215] op_sel_hi:[1,0]
	v_pk_mul_f32 v[6:7], v[6:7], v[214:215] op_sel_hi:[1,0]
	v_pk_mul_f32 v[142:143], v[12:13], v[216:217] op_sel_hi:[1,0]
	v_pk_mul_f32 v[158:159], v[14:15], v[216:217] op_sel_hi:[1,0]
	v_pk_mul_f32 v[188:189], v[4:5], v[216:217] op_sel_hi:[1,0]
	v_pk_mul_f32 v[192:193], v[6:7], v[216:217] op_sel_hi:[1,0]
	v_exp_f32_e32 v142, v142
	v_exp_f32_e32 v143, v143
	v_exp_f32_e32 v158, v158
	v_exp_f32_e32 v159, v159
	v_exp_f32_e32 v188, v188
	v_exp_f32_e32 v189, v189
	v_exp_f32_e32 v192, v192
	v_exp_f32_e32 v193, v193
	v_pk_mul_f32 v[8:9], v[8:9], v[214:215] op_sel_hi:[1,0]
	v_pk_mul_f32 v[10:11], v[10:11], v[214:215] op_sel_hi:[1,0]
	v_pk_mul_f32 v[0:1], v[0:1], v[214:215] op_sel_hi:[1,0]
	v_pk_mul_f32 v[2:3], v[2:3], v[214:215] op_sel_hi:[1,0]
	v_pk_add_f32 v[142:143], v[142:143], v[204:205] op_sel_hi:[1,0]
	v_pk_add_f32 v[158:159], v[158:159], v[204:205] op_sel_hi:[1,0]
	v_pk_add_f32 v[188:189], v[188:189], v[204:205] op_sel_hi:[1,0]
	v_pk_add_f32 v[192:193], v[192:193], v[204:205] op_sel_hi:[1,0]
	v_rcp_f32_e32 v142, v142
	v_rcp_f32_e32 v143, v143
	v_rcp_f32_e32 v158, v158
	v_rcp_f32_e32 v159, v159
	v_rcp_f32_e32 v188, v188
	v_rcp_f32_e32 v189, v189
	v_rcp_f32_e32 v192, v192
	v_rcp_f32_e32 v193, v193
	v_mad_i64_i32 v[230:231], s[10:11], v128, s53, v[226:227]
	v_lshl_add_u64 v[230:231], v[230:231], 0, v[228:229]
	v_pk_mul_f32 v[142:143], v[12:13], v[142:143]
	v_pk_mul_f32 v[158:159], v[14:15], v[158:159]
	v_pk_mul_f32 v[188:189], v[4:5], v[188:189]
	v_pk_mul_f32 v[192:193], v[6:7], v[192:193]
	v_pk_mul_f32 v[8:9], v[8:9], v[142:143]
	v_pk_mul_f32 v[10:11], v[10:11], v[158:159]
	v_pk_mul_f32 v[0:1], v[0:1], v[188:189]
	v_pk_mul_f32 v[2:3], v[2:3], v[192:193]
	v_cvt_pk_bf16_f32 v232, v8, v9
	v_cvt_pk_bf16_f32 v233, v10, v11
	v_cvt_pk_bf16_f32 v234, v0, v1
	v_cvt_pk_bf16_f32 v235, v2, v3
	global_store_dwordx4 v[230:231], v[232:235], off
	s_andn2_b64 vcc, exec, s[8:9]
	s_mov_b64 s[8:9], -1
	s_cbranch_vccnz .LBB0_488
	s_branch .LBB0_620
